# selected-branch near-diagonal half tiles: 16 bias-LUT gathers kept 8 deep in flight, issued from inside the QK MFMA chain (was one LDS round trip per element)
# speedup vs baseline: 1.0181x; 1.0080x over previous
; DI float xor32_max(float x) { const auto r_ = __builtin_amdgcn_permlane32_swap(__float_as_uint(x), __float_as_uint(x), false, false); return fmaxf(__uint_as_float(r_[0]), __uint_as_float(r_[1])); }
; #define MFMA32(a, b, c) __builtin_amdgcn_mfma_f32_32x32x16_bf16((a), (b), (c), 0, 0, 0)
; DI int crow(int i, int hh) { return (i & 3) + 8 * (i >> 2) + 4 * hh; }
; template <int MODE, bool FAR>
; DI void attn_tile(const unsigned char* kl  , const unsigned char* vl  ,
;                   int k0, int tq, int r, int hh, bool bit, const bf16x8 (&qf)[8], const float* lutH, f32x16 (&o)[4], float& m, float& l) {
;     ...
;     const unsigned char* kp = kl + r * 272 + 16 * hh;
; #pragma unroll
;     for (int kk = 0; kk < 8; ++kk) { const bf16x8 a = *(const bf16x8*)(kp + 32 * kk); s = MFMA32(a, qf[kk], s); }
;     float tmax = NEGF;
;     if (FAR) {
;         const float b31 = lutH[255];
; #pragma unroll
;         for (int i = 0; i < 16; ++i) { const float v = s[i] * QK_C1 + b31; s[i] = (MODE == 0 && !bit) ? NEGF : v; tmax = fmaxf(tmax, s[i]); }
;     } else {
; #pragma unroll
;         for (int i = 0; i < 16; ++i) { const int dist = tq - (k0 + crow(i, hh));
;             const bool valid = MODE == 0 ? (bit && dist >= 0) : (dist >= 0 && dist < 512);
;             const int di = dist < 0 ? 0 : (dist > 255 ? 255 : dist);
;             const float v = s[i] * QK_C1 + lutH[di];
;             s[i] = valid ? v : NEGF; tmax = fmaxf(tmax, s[i]); }
;     }
;     tmax = xor32_max(tmax);
;     const float mnew = fmaxf(m, tmax);
;     if (__ballot(mnew != m) != 0ull) {
.LBB0_798:
	s_andn2_saveexec_b64 s[22:23], s[22:23]
	s_cbranch_execz .LBB0_791
	v_or_b32_e32 v242, v214, v170
	s_waitcnt lgkmcnt(7)
	v_mfma_f32_32x32x16_bf16 v[82:97], v[82:85], v[114:117], 0
	v_sub_u32_e32 v224, v201, v242
	s_nop 0
	v_med3_i32 v233, v224, 0, v194
	v_lshl_add_u32 v233, v233, 2, v202
	ds_read_b32 v233, v233
	s_waitcnt lgkmcnt(7)
	v_mfma_f32_32x32x16_bf16 v[82:97], v[110:113], v[118:121], v[82:97]
	v_or_b32_e32 v225, 1, v242
	v_sub_u32_e32 v225, v201, v225
	v_med3_i32 v234, v225, 0, v194
	v_lshl_add_u32 v234, v234, 2, v202
	ds_read_b32 v234, v234
	s_waitcnt lgkmcnt(7)
	v_mfma_f32_32x32x16_bf16 v[82:97], v[106:109], v[122:125], v[82:97]
	v_or_b32_e32 v226, 2, v242
	v_sub_u32_e32 v226, v201, v226
	v_med3_i32 v235, v226, 0, v194
	v_lshl_add_u32 v235, v235, 2, v202
	ds_read_b32 v235, v235
	s_waitcnt lgkmcnt(7)
	v_mfma_f32_32x32x16_bf16 v[82:97], v[102:105], v[126:129], v[82:97]
	v_or_b32_e32 v227, 3, v242
	v_sub_u32_e32 v227, v201, v227
	v_med3_i32 v236, v227, 0, v194
	v_lshl_add_u32 v236, v236, 2, v202
	ds_read_b32 v236, v236
	s_waitcnt lgkmcnt(7)
	v_mfma_f32_32x32x16_bf16 v[82:97], v[98:101], v[130:133], v[82:97]
	v_or_b32_e32 v228, 8, v242
	v_sub_u32_e32 v228, v201, v228
	v_med3_i32 v237, v228, 0, v194
	v_lshl_add_u32 v237, v237, 2, v202
	ds_read_b32 v237, v237
	s_waitcnt lgkmcnt(7)
	v_mfma_f32_32x32x16_bf16 v[82:97], v[12:15], v[134:137], v[82:97]
	v_or_b32_e32 v229, 9, v242
	v_sub_u32_e32 v229, v201, v229
	v_med3_i32 v238, v229, 0, v194
	v_lshl_add_u32 v238, v238, 2, v202
	ds_read_b32 v238, v238
	s_waitcnt lgkmcnt(7)
	v_mfma_f32_32x32x16_bf16 v[82:97], v[8:11], v[138:141], v[82:97]
	v_or_b32_e32 v230, 10, v242
	v_sub_u32_e32 v230, v201, v230
	v_med3_i32 v239, v230, 0, v194
	v_lshl_add_u32 v239, v239, 2, v202
	ds_read_b32 v239, v239
	s_waitcnt lgkmcnt(7)
	v_mfma_f32_32x32x16_bf16 v[82:97], v[4:7], v[142:145], v[82:97]
	v_or_b32_e32 v231, 11, v242
	v_sub_u32_e32 v231, v201, v231
	v_med3_i32 v240, v231, 0, v194
	v_lshl_add_u32 v240, v240, 2, v202
	ds_read_b32 v240, v240
	s_nop 6
	s_waitcnt lgkmcnt(7)
	v_cmp_lt_i32_e32 vcc, -1, v224
	v_fmac_f32_e32 v233, 0x3e0293ee, v82
	v_or_b32_e32 v232, 16, v242
	s_and_b64 vcc, s[10:11], vcc
	v_sub_u32_e32 v232, v201, v232
	v_med3_i32 v241, v232, 0, v194
	v_cndmask_b32_e32 v4, v195, v233, vcc
	v_lshl_add_u32 v241, v241, 2, v202
	ds_read_b32 v241, v241
	s_waitcnt lgkmcnt(7)
	v_cmp_lt_i32_e32 vcc, -1, v225
	v_fmac_f32_e32 v234, 0x3e0293ee, v83
	v_or_b32_e32 v224, 17, v242
	s_and_b64 vcc, s[10:11], vcc
	v_sub_u32_e32 v224, v201, v224
	v_med3_i32 v233, v224, 0, v194
	v_cndmask_b32_e32 v5, v195, v234, vcc
	v_lshl_add_u32 v233, v233, 2, v202
	ds_read_b32 v233, v233
	v_max3_f32 v243, v4, s49, v5
	s_waitcnt lgkmcnt(7)
	v_cmp_lt_i32_e32 vcc, -1, v226
	v_fmac_f32_e32 v235, 0x3e0293ee, v84
	v_or_b32_e32 v225, 18, v242
	s_and_b64 vcc, s[10:11], vcc
	v_sub_u32_e32 v225, v201, v225
	v_med3_i32 v234, v225, 0, v194
	v_cndmask_b32_e32 v6, v195, v235, vcc
	v_lshl_add_u32 v234, v234, 2, v202
	ds_read_b32 v234, v234
	s_waitcnt lgkmcnt(7)
	v_cmp_lt_i32_e32 vcc, -1, v227
	v_fmac_f32_e32 v236, 0x3e0293ee, v85
	v_or_b32_e32 v226, 19, v242
	s_and_b64 vcc, s[10:11], vcc
	v_sub_u32_e32 v226, v201, v226
	v_med3_i32 v235, v226, 0, v194
	v_cndmask_b32_e32 v7, v195, v236, vcc
	v_lshl_add_u32 v235, v235, 2, v202
	ds_read_b32 v235, v235
	v_max3_f32 v243, v243, v6, v7
	s_waitcnt lgkmcnt(7)
	v_cmp_lt_i32_e32 vcc, -1, v228
	v_fmac_f32_e32 v237, 0x3e0293ee, v86
	v_or_b32_e32 v227, 24, v242
	s_and_b64 vcc, s[10:11], vcc
	v_sub_u32_e32 v227, v201, v227
	v_med3_i32 v236, v227, 0, v194
	v_cndmask_b32_e32 v8, v195, v237, vcc
	v_lshl_add_u32 v236, v236, 2, v202
	ds_read_b32 v236, v236
	s_waitcnt lgkmcnt(7)
	v_cmp_lt_i32_e32 vcc, -1, v229
	v_fmac_f32_e32 v238, 0x3e0293ee, v87
	v_or_b32_e32 v228, 25, v242
	s_and_b64 vcc, s[10:11], vcc
	v_sub_u32_e32 v228, v201, v228
	v_med3_i32 v237, v228, 0, v194
	v_cndmask_b32_e32 v9, v195, v238, vcc
	v_lshl_add_u32 v237, v237, 2, v202
	ds_read_b32 v237, v237
	v_max3_f32 v243, v243, v8, v9
	s_waitcnt lgkmcnt(7)
	v_cmp_lt_i32_e32 vcc, -1, v230
	v_fmac_f32_e32 v239, 0x3e0293ee, v88
	v_or_b32_e32 v229, 26, v242
	s_and_b64 vcc, s[10:11], vcc
	v_sub_u32_e32 v229, v201, v229
	v_med3_i32 v238, v229, 0, v194
	v_cndmask_b32_e32 v10, v195, v239, vcc
	v_lshl_add_u32 v238, v238, 2, v202
	ds_read_b32 v238, v238
	s_waitcnt lgkmcnt(7)
	v_cmp_lt_i32_e32 vcc, -1, v231
	v_fmac_f32_e32 v240, 0x3e0293ee, v89
	v_or_b32_e32 v230, 27, v242
	s_and_b64 vcc, s[10:11], vcc
	v_sub_u32_e32 v230, v201, v230
	v_med3_i32 v239, v230, 0, v194
	v_cndmask_b32_e32 v12, v195, v240, vcc
	v_lshl_add_u32 v239, v239, 2, v202
	ds_read_b32 v239, v239
	v_max3_f32 v243, v243, v10, v12
	s_waitcnt lgkmcnt(7)
	v_cmp_lt_i32_e32 vcc, -1, v232
	v_fmac_f32_e32 v241, 0x3e0293ee, v90
	s_nop 0
	s_and_b64 vcc, s[10:11], vcc
	s_nop 0
	s_nop 0
	v_cndmask_b32_e32 v13, v195, v241, vcc
	s_waitcnt lgkmcnt(6)
	v_cmp_lt_i32_e32 vcc, -1, v224
	v_fmac_f32_e32 v233, 0x3e0293ee, v91
	s_nop 0
	s_and_b64 vcc, s[10:11], vcc
	s_nop 0
	s_nop 0
	v_cndmask_b32_e32 v14, v195, v233, vcc
	v_max3_f32 v243, v243, v13, v14
	s_waitcnt lgkmcnt(5)
	v_cmp_lt_i32_e32 vcc, -1, v225
	v_fmac_f32_e32 v234, 0x3e0293ee, v92
	s_nop 0
	s_and_b64 vcc, s[10:11], vcc
	s_nop 0
	s_nop 0
	v_cndmask_b32_e32 v15, v195, v234, vcc
	s_waitcnt lgkmcnt(4)
	v_cmp_lt_i32_e32 vcc, -1, v226
	v_fmac_f32_e32 v235, 0x3e0293ee, v93
	s_nop 0
	s_and_b64 vcc, s[10:11], vcc
	s_nop 0
	s_nop 0
	v_cndmask_b32_e32 v82, v195, v235, vcc
	v_max3_f32 v243, v243, v15, v82
	s_waitcnt lgkmcnt(3)
	v_cmp_lt_i32_e32 vcc, -1, v227
	v_fmac_f32_e32 v236, 0x3e0293ee, v94
	s_nop 0
	s_and_b64 vcc, s[10:11], vcc
	s_nop 0
	s_nop 0
	v_cndmask_b32_e32 v83, v195, v236, vcc
	s_waitcnt lgkmcnt(2)
	v_cmp_lt_i32_e32 vcc, -1, v228
	v_fmac_f32_e32 v237, 0x3e0293ee, v95
	s_nop 0
	s_and_b64 vcc, s[10:11], vcc
	s_nop 0
	s_nop 0
	v_cndmask_b32_e32 v84, v195, v237, vcc
	v_max3_f32 v243, v243, v83, v84
	s_waitcnt lgkmcnt(1)
	v_cmp_lt_i32_e32 vcc, -1, v229
	v_fmac_f32_e32 v238, 0x3e0293ee, v96
	s_nop 0
	s_and_b64 vcc, s[10:11], vcc
	s_nop 0
	s_nop 0
	v_cndmask_b32_e32 v85, v195, v238, vcc
	s_waitcnt lgkmcnt(0)
	v_cmp_lt_i32_e32 vcc, -1, v230
	v_fmac_f32_e32 v239, 0x3e0293ee, v97
	s_nop 0
	s_and_b64 vcc, s[10:11], vcc
	s_nop 0
	s_nop 0
	v_cndmask_b32_e32 v11, v195, v239, vcc
	v_max3_f32 v86, v243, v85, v11
	v_mov_b32_e32 v87, v86
	s_nop 1
	v_permlane32_swap_b32_e32 v86, v87
	v_max3_f32 v86, v212, v86, v87
	v_cmp_neq_f32_e32 vcc, v86, v212
	s_cbranch_vccz .LBB0_790
; template <int MODE, bool FAR>
; DI void attn_tile(const unsigned char* kl  , const unsigned char* vl  ,
;                   int k0, int tq, int r, int hh, bool bit, const bf16x8 (&qf)[8], const float* lutH, f32x16 (&o)[4], float& m, float& l) {
;     ...
;     if (__ballot(mnew != m) != 0ull) {
;         const float alpha = __builtin_amdgcn_exp2f(m - mnew);
;         l *= alpha; m = mnew;
; #pragma unroll
;         for (int dt = 0; dt < 4; ++dt)
; #pragma unroll
;             for (int i = 0; i < 16; ++i) o[dt][i] *= alpha;
;     }
	v_sub_f32_e32 v87, v212, v86
	v_exp_f32_e32 v88, v87
	v_mov_b32_e32 v212, v86
	v_mul_f32_e32 v181, v181, v88
	v_pk_mul_f32 v[80:81], v[80:81], v[88:89] op_sel_hi:[1,0]
	v_pk_mul_f32 v[78:79], v[78:79], v[88:89] op_sel_hi:[1,0]
	v_pk_mul_f32 v[76:77], v[76:77], v[88:89] op_sel_hi:[1,0]
	v_pk_mul_f32 v[74:75], v[74:75], v[88:89] op_sel_hi:[1,0]
	v_pk_mul_f32 v[72:73], v[72:73], v[88:89] op_sel_hi:[1,0]
	v_pk_mul_f32 v[70:71], v[70:71], v[88:89] op_sel_hi:[1,0]
	v_pk_mul_f32 v[68:69], v[68:69], v[88:89] op_sel_hi:[1,0]
	v_pk_mul_f32 v[66:67], v[66:67], v[88:89] op_sel_hi:[1,0]
	v_pk_mul_f32 v[64:65], v[64:65], v[88:89] op_sel_hi:[1,0]
	v_pk_mul_f32 v[62:63], v[62:63], v[88:89] op_sel_hi:[1,0]
	v_pk_mul_f32 v[60:61], v[60:61], v[88:89] op_sel_hi:[1,0]
	v_pk_mul_f32 v[58:59], v[58:59], v[88:89] op_sel_hi:[1,0]
	v_pk_mul_f32 v[56:57], v[56:57], v[88:89] op_sel_hi:[1,0]
	v_pk_mul_f32 v[54:55], v[54:55], v[88:89] op_sel_hi:[1,0]
	v_pk_mul_f32 v[52:53], v[52:53], v[88:89] op_sel_hi:[1,0]
	v_pk_mul_f32 v[50:51], v[50:51], v[88:89] op_sel_hi:[1,0]
	v_pk_mul_f32 v[48:49], v[48:49], v[88:89] op_sel_hi:[1,0]
	v_pk_mul_f32 v[46:47], v[46:47], v[88:89] op_sel_hi:[1,0]
	v_pk_mul_f32 v[44:45], v[44:45], v[88:89] op_sel_hi:[1,0]
	v_pk_mul_f32 v[42:43], v[42:43], v[88:89] op_sel_hi:[1,0]
	v_pk_mul_f32 v[40:41], v[40:41], v[88:89] op_sel_hi:[1,0]
	v_pk_mul_f32 v[38:39], v[38:39], v[88:89] op_sel_hi:[1,0]
	v_pk_mul_f32 v[36:37], v[36:37], v[88:89] op_sel_hi:[1,0]
	v_pk_mul_f32 v[34:35], v[34:35], v[88:89] op_sel_hi:[1,0]
	v_pk_mul_f32 v[32:33], v[32:33], v[88:89] op_sel_hi:[1,0]
	v_pk_mul_f32 v[30:31], v[30:31], v[88:89] op_sel_hi:[1,0]
	v_pk_mul_f32 v[28:29], v[28:29], v[88:89] op_sel_hi:[1,0]
	v_pk_mul_f32 v[26:27], v[26:27], v[88:89] op_sel_hi:[1,0]
	v_pk_mul_f32 v[24:25], v[24:25], v[88:89] op_sel_hi:[1,0]
	v_pk_mul_f32 v[22:23], v[22:23], v[88:89] op_sel_hi:[1,0]
	v_pk_mul_f32 v[20:21], v[20:21], v[88:89] op_sel_hi:[1,0]
	v_pk_mul_f32 v[18:19], v[18:19], v[88:89] op_sel_hi:[1,0]
	s_branch .LBB0_790
